# phase-0 x to bf16 conversion: the four row loads issued together with counted waits
# speedup vs baseline: 1.0678x; 1.0059x over previous
.LBB0_788:
	s_waitcnt lgkmcnt(0)
	global_load_dwordx4 v[14:17], v[6:7], off offset:-3072
	global_load_dwordx4 v[22:25], v[6:7], off offset:-2048
	global_load_dwordx4 v[26:29], v[6:7], off offset:-1024
	global_load_dwordx4 v[30:33], v[6:7], off
	v_lshl_add_u64 v[18:19], s[80:81], 0, v[4:5]
	s_mov_b32 s2, 0x4200000
	v_add_co_u32_e32 v18, vcc, s2, v18
	s_waitcnt vmcnt(3)
	v_cvt_pk_bf16_f32 v34, v14, v15
	v_addc_co_u32_e32 v19, vcc, 0, v19, vcc
	v_cvt_pk_bf16_f32 v35, v16, v17
	global_store_dwordx2 v[18:19], v[34:35], off
	v_mul_f32_e32 v1, v15, v15
	v_fmac_f32_e32 v1, v14, v14
	v_fmac_f32_e32 v1, v16, v16
	v_fmac_f32_e32 v1, v17, v17
	s_waitcnt vmcnt(3)
	v_cvt_pk_bf16_f32 v36, v22, v23
	v_cvt_pk_bf16_f32 v37, v24, v25
	global_store_dwordx2 v[18:19], v[36:37], off offset:512
	v_mul_f32_e32 v14, v23, v23
	v_fmac_f32_e32 v14, v22, v22
	v_fmac_f32_e32 v14, v24, v24
	v_fmac_f32_e32 v14, v25, v25
	v_add_f32_e32 v1, v1, v14
	s_waitcnt vmcnt(3)
	v_cvt_pk_bf16_f32 v38, v26, v27
	v_cvt_pk_bf16_f32 v39, v28, v29
	global_store_dwordx2 v[18:19], v[38:39], off offset:1024
	v_mul_f32_e32 v14, v27, v27
	v_fmac_f32_e32 v14, v26, v26
	v_fmac_f32_e32 v14, v28, v28
	v_fmac_f32_e32 v14, v29, v29
	v_add_f32_e32 v1, v1, v14
	s_waitcnt vmcnt(3)
	v_mul_f32_e32 v14, v31, v31
	v_fmac_f32_e32 v14, v30, v30
	v_fmac_f32_e32 v14, v32, v32
	v_fmac_f32_e32 v14, v33, v33
	v_add_f32_e32 v1, v1, v14
	ds_bpermute_b32 v14, v8, v1
	v_cvt_pk_bf16_f32 v40, v30, v31
	v_cvt_pk_bf16_f32 v41, v32, v33
	global_store_dwordx2 v[18:19], v[40:41], off offset:1536
	s_waitcnt lgkmcnt(0)
	v_add_f32_e32 v1, v1, v14
	ds_bpermute_b32 v14, v9, v1
	s_waitcnt lgkmcnt(0)
	v_add_f32_e32 v1, v1, v14
	ds_bpermute_b32 v14, v10, v1
	s_waitcnt lgkmcnt(0)
	v_add_f32_e32 v1, v1, v14
	ds_bpermute_b32 v14, v11, v1
	s_waitcnt lgkmcnt(0)
	v_add_f32_e32 v1, v1, v14
	ds_bpermute_b32 v14, v12, v1
	s_waitcnt lgkmcnt(0)
	v_add_f32_e32 v1, v1, v14
	ds_bpermute_b32 v14, v13, v1
	s_and_saveexec_b64 s[16:17], s[4:5]
	s_cbranch_execz .LBB0_787
	s_waitcnt lgkmcnt(0)
	v_add_f32_e32 v1, v1, v14
	v_fma_f32 v1, v1, s82, 0.5
	v_trunc_f32_e32 v1, v1
	v_mul_f32_e32 v14, 0x2f800000, v1
	v_floor_f32_e32 v15, v14
	v_fmac_f32_e32 v1, 0xcf800000, v15
	v_cvt_u32_f32_e32 v14, v1
	v_cvt_u32_f32_e32 v15, v15
	v_lshl_add_u64 v[16:17], s[80:81], 0, v[2:3]
	flat_store_dwordx2 v[16:17], v[14:15]
	s_branch .LBB0_787
